# C loop: leftover PV MFMA issued right after the barrier ahead of the LDS-DMA issue (on top of A SGPR-base DMA restructure)
# baseline (speedup 1.0000x reference)
.LBB0_541:
	v_lshl_add_u64 v[164:165], v[160:161], 0, v[172:173]
	s_add_i32 s10, s0, 0xf000
	v_lshl_add_u64 v[96:97], v[164:165], 0, s[12:13]
	s_mov_b32 m0, s10
	v_lshl_add_u64 v[166:167], v[158:159], 0, v[172:173]
	global_load_lds_dwordx4 v[96:97], off
	v_lshl_add_u64 v[96:97], v[166:167], 0, s[14:15]
	s_mov_b32 m0, s8
	s_nop 0
	global_load_lds_dwordx4 v[96:97], off
	ds_read_b128 v[96:99], v201 offset:20480
	ds_read_b128 v[144:147], v201 offset:24576
	ds_read_b128 v[100:103], v202 offset:20480
	ds_read_b128 v[168:171], v202 offset:24576
	v_exp_f32_e32 v180, v80
	v_exp_f32_e32 v181, v81
	v_exp_f32_e32 v182, v82
	v_exp_f32_e32 v183, v83
	s_waitcnt lgkmcnt(0)
	v_mfma_f32_32x32x16_bf16 v[112:127], v[96:99], v[132:135], v[48:63]
	ds_read_b128 v[80:83], v204 offset:20480
	ds_read_b128 v[174:177], v204 offset:24576
	v_exp_f32_e32 v84, v84
	v_exp_f32_e32 v85, v85
	v_exp_f32_e32 v86, v86
	v_exp_f32_e32 v87, v87
	v_mfma_f32_32x32x16_bf16 v[112:127], v[100:103], v[128:131], v[112:127]
	v_cvt_pk_bf16_f32 v180, v180, v181
	v_cvt_pk_bf16_f32 v181, v182, v183
	v_cvt_pk_bf16_f32 v182, v84, v85
	v_cvt_pk_bf16_f32 v183, v86, v87
	v_mfma_f32_32x32x16_bf16 v[96:111], v[144:147], v[132:135], v[48:63]
	ds_read_b128 v[84:87], v203 offset:20480
	ds_read_b128 v[144:147], v203 offset:24576
	s_waitcnt lgkmcnt(0)
	v_mfma_f32_32x32x16_bf16 v[112:127], v[80:83], v[140:143], v[112:127]
	v_exp_f32_e32 v80, v88
	v_exp_f32_e32 v81, v89
	v_exp_f32_e32 v82, v90
	v_exp_f32_e32 v83, v91
	v_mfma_f32_32x32x16_bf16 v[112:127], v[84:87], v[136:139], v[112:127]
	v_exp_f32_e32 v84, v92
	v_exp_f32_e32 v85, v93
	v_exp_f32_e32 v86, v94
	v_exp_f32_e32 v87, v95
	v_mfma_f32_32x32x16_bf16 v[96:111], v[168:171], v[128:131], v[96:111]
	v_cvt_pk_bf16_f32 v168, v80, v81
	v_cvt_pk_bf16_f32 v169, v82, v83
	v_cvt_pk_bf16_f32 v170, v84, v85
	v_cvt_pk_bf16_f32 v171, v86, v87
	ds_read_b128 v[80:83], v206 offset:8192
	ds_read_b128 v[84:87], v206 offset:12288
	v_mfma_f32_32x32x16_bf16 v[96:111], v[174:177], v[140:143], v[96:111]
	s_waitcnt lgkmcnt(0)
	v_mfma_f32_32x32x16_bf16 v[0:15], v[84:87], v[180:183], v[0:15]
	ds_read_b128 v[88:91], v205 offset:8192
	ds_read_b128 v[92:95], v205 offset:12288
	v_exp_f32_e32 v217, v64
	v_exp_f32_e32 v218, v65
	v_exp_f32_e32 v219, v66
	v_exp_f32_e32 v216, v67
	v_exp_f32_e32 v221, v68
	v_exp_f32_e32 v222, v69
	v_mfma_f32_32x32x16_bf16 v[16:31], v[80:83], v[180:183], v[16:31]
	v_exp_f32_e32 v223, v70
	v_exp_f32_e32 v220, v71
	v_cvt_pk_bf16_f32 v64, v217, v218
	v_cvt_pk_bf16_f32 v65, v219, v216
	v_cvt_pk_bf16_f32 v66, v221, v222
	v_cvt_pk_bf16_f32 v67, v223, v220
	s_waitcnt lgkmcnt(0)
	v_mfma_f32_32x32x16_bf16 v[0:15], v[92:95], v[168:171], v[0:15]
	ds_read_b128 v[68:71], v200 offset:8192
	ds_read_b128 v[174:177], v200 offset:12288
	v_exp_f32_e32 v225, v72
	v_exp_f32_e32 v226, v73
	v_exp_f32_e32 v227, v74
	v_exp_f32_e32 v224, v75
	v_exp_f32_e32 v229, v76
	v_exp_f32_e32 v230, v77
	v_mfma_f32_32x32x16_bf16 v[16:31], v[88:91], v[168:171], v[16:31]
	v_exp_f32_e32 v231, v78
	v_exp_f32_e32 v228, v79
	v_cvt_pk_bf16_f32 v72, v225, v226
	v_cvt_pk_bf16_f32 v73, v227, v224
	v_cvt_pk_bf16_f32 v74, v229, v230
	v_cvt_pk_bf16_f32 v75, v231, v228
	v_mfma_f32_32x32x16_bf16 v[96:111], v[144:147], v[136:139], v[96:111]
	s_waitcnt lgkmcnt(0)
	v_mfma_f32_32x32x16_bf16 v[16:31], v[68:71], v[64:67], v[16:31]
	ds_read_b128 v[76:79], v151 offset:8192
	ds_read_b128 v[184:187], v151 offset:12288
	s_waitcnt lgkmcnt(0)
	v_mfma_f32_32x32x16_bf16 v[16:31], v[76:79], v[72:75], v[16:31]
	s_waitcnt vmcnt(2)
	s_mov_b32 m0, s0
	s_waitcnt lgkmcnt(0)
	s_barrier
	v_mfma_f32_32x32x16_bf16 v[0:15], v[174:177], v[64:67], v[0:15]
	v_lshl_add_u64 v[68:69], v[164:165], 0, s[16:17]
	global_load_lds_dwordx4 v[68:69], off
	v_lshl_add_u64 v[68:69], v[166:167], 0, s[18:19]
	s_mov_b32 m0, s1
	s_nop 0
	global_load_lds_dwordx4 v[68:69], off
	ds_read_b128 v[68:71], v201 offset:40960
	ds_read_b128 v[188:191], v201 offset:45056
	v_mov_b64_e32 v[146:147], s[38:39]
	v_mov_b64_e32 v[144:145], s[36:37]
	ds_read_b128 v[64:67], v202 offset:40960
	ds_read_b128 v[174:177], v202 offset:45056
	v_exp_f32_e32 v192, v112
	v_exp_f32_e32 v193, v113
	v_exp_f32_e32 v194, v114
	v_exp_f32_e32 v195, v115
	s_waitcnt lgkmcnt(0)
	v_mfma_f32_32x32x16_bf16 v[80:95], v[68:71], v[132:135], v[48:63]
	v_mfma_f32_32x32x16_bf16 v[32:47], v[144:147], v[180:183], v[32:47]
	v_mfma_f32_32x32x16_bf16 v[0:15], v[184:187], v[72:75], v[0:15]
	v_mfma_f32_32x32x16_bf16 v[80:95], v[64:67], v[128:131], v[80:95]
	ds_read_b128 v[112:115], v204 offset:40960
	ds_read_b128 v[180:183], v204 offset:45056
	v_exp_f32_e32 v116, v116
	v_exp_f32_e32 v117, v117
	v_exp_f32_e32 v118, v118
	v_exp_f32_e32 v119, v119
	v_cvt_pk_bf16_f32 v192, v192, v193
	v_cvt_pk_bf16_f32 v193, v194, v195
	v_mfma_f32_32x32x16_bf16 v[64:79], v[188:191], v[132:135], v[48:63]
	v_cvt_pk_bf16_f32 v194, v116, v117
	v_cvt_pk_bf16_f32 v195, v118, v119
	s_waitcnt lgkmcnt(0)
	v_mfma_f32_32x32x16_bf16 v[80:95], v[112:115], v[140:143], v[80:95]
	ds_read_b128 v[112:115], v203 offset:40960
	ds_read_b128 v[116:119], v203 offset:45056
	v_exp_f32_e32 v120, v120
	v_exp_f32_e32 v121, v121
	v_exp_f32_e32 v122, v122
	v_exp_f32_e32 v123, v123
	v_mfma_f32_32x32x16_bf16 v[32:47], v[144:147], v[168:171], v[32:47]
	v_mfma_f32_32x32x16_bf16 v[64:79], v[174:177], v[128:131], v[64:79]
	v_cvt_pk_bf16_f32 v174, v120, v121
	v_cvt_pk_bf16_f32 v175, v122, v123
	s_waitcnt lgkmcnt(0)
	v_mfma_f32_32x32x16_bf16 v[80:95], v[112:115], v[136:139], v[80:95]
	v_exp_f32_e32 v112, v124
	v_exp_f32_e32 v113, v125
	v_exp_f32_e32 v114, v126
	v_exp_f32_e32 v115, v127
	v_cvt_pk_bf16_f32 v176, v112, v113
	v_cvt_pk_bf16_f32 v177, v114, v115
	v_mfma_f32_32x32x16_bf16 v[64:79], v[180:183], v[140:143], v[64:79]
	ds_read_b128 v[112:115], v206 offset:28672
	ds_read_b128 v[120:123], v206 offset:32768
	s_waitcnt lgkmcnt(0)
	v_mfma_f32_32x32x16_bf16 v[0:15], v[120:123], v[192:195], v[0:15]
	ds_read_b128 v[124:127], v205 offset:28672
	ds_read_b128 v[180:183], v205 offset:32768
	v_exp_f32_e32 v121, v96
	v_exp_f32_e32 v96, v97
	v_exp_f32_e32 v97, v98
	v_pk_add_f32 v[122:123], v[162:163], v[218:219]
	v_exp_f32_e32 v120, v99
	v_pk_add_f32 v[98:99], v[156:157], v[216:217]
	v_mfma_f32_32x32x16_bf16 v[16:31], v[112:115], v[192:195], v[16:31]
	v_add_f32_e64 v122, v222, v122
	v_add_f32_e64 v123, v223, v123
	v_add_f32_e64 v98, v220, v98
	v_add_f32_e64 v99, v221, v99
	v_exp_f32_e32 v163, v100
	v_exp_f32_e32 v184, v101
	v_exp_f32_e32 v185, v102
	v_exp_f32_e32 v162, v103
	v_pk_add_f32 v[122:123], v[226:227], v[122:123]
	v_pk_add_f32 v[98:99], v[224:225], v[98:99]
	v_pk_add_f32 v[122:123], v[230:231], v[122:123]
	v_pk_add_f32 v[98:99], v[228:229], v[98:99]
	v_pk_add_f32 v[168:169], v[122:123], v[96:97]
	v_pk_add_f32 v[156:157], v[98:99], v[120:121]
	v_cvt_pk_bf16_f32 v96, v121, v96
	v_cvt_pk_bf16_f32 v97, v97, v120
	v_cvt_pk_bf16_f32 v98, v163, v184
	v_cvt_pk_bf16_f32 v99, v185, v162
	s_waitcnt lgkmcnt(0)
	v_mfma_f32_32x32x16_bf16 v[0:15], v[180:183], v[174:177], v[0:15]
	ds_read_b128 v[100:103], v200 offset:28672
	ds_read_b128 v[180:183], v200 offset:32768
	v_exp_f32_e32 v171, v104
	v_exp_f32_e32 v188, v105
	v_exp_f32_e32 v189, v106
	v_exp_f32_e32 v170, v107
	v_exp_f32_e32 v187, v108
	v_exp_f32_e32 v190, v109
	v_mfma_f32_32x32x16_bf16 v[64:79], v[116:119], v[136:139], v[64:79]
	v_exp_f32_e32 v191, v110
	v_exp_f32_e32 v186, v111
	v_cvt_pk_bf16_f32 v104, v171, v188
	v_cvt_pk_bf16_f32 v105, v189, v170
	v_cvt_pk_bf16_f32 v106, v187, v190
	v_cvt_pk_bf16_f32 v107, v191, v186
	v_mfma_f32_32x32x16_bf16 v[16:31], v[124:127], v[174:177], v[16:31]
	s_waitcnt lgkmcnt(0)
	v_mfma_f32_32x32x16_bf16 v[16:31], v[100:103], v[96:99], v[16:31]
	ds_read_b128 v[108:111], v151 offset:28672
	ds_read_b128 v[218:221], v151 offset:32768
	s_waitcnt lgkmcnt(0)
	v_mfma_f32_32x32x16_bf16 v[16:31], v[108:111], v[104:107], v[16:31]
	s_waitcnt vmcnt(2)
	s_mov_b32 m0, s4
	s_waitcnt lgkmcnt(0)
	s_barrier
	v_mfma_f32_32x32x16_bf16 v[0:15], v[180:183], v[96:99], v[0:15]
	v_lshl_add_u64 v[100:101], v[164:165], 0, s[34:35]
	global_load_lds_dwordx4 v[100:101], off
	v_lshl_add_u64 v[100:101], v[166:167], 0, s[42:43]
	s_mov_b32 m0, s5
	s_add_i32 s11, 0, 0x10000
	global_load_lds_dwordx4 v[100:101], off
	v_add_u32_e32 v215, s11, v207
	ds_read_b128 v[100:103], v201 offset:61440
	ds_read_b128 v[222:225], v215
	v_add_u32_e32 v216, s11, v208
	ds_read_b128 v[96:99], v202 offset:61440
	ds_read_b128 v[180:183], v216
	v_exp_f32_e32 v226, v80
	v_exp_f32_e32 v227, v81
	v_exp_f32_e32 v228, v82
	v_exp_f32_e32 v229, v83
	v_mfma_f32_32x32x16_bf16 v[32:47], v[144:147], v[192:195], v[32:47]
	v_mfma_f32_32x32x16_bf16 v[0:15], v[218:221], v[104:107], v[0:15]
	s_waitcnt lgkmcnt(0)
	v_mfma_f32_32x32x16_bf16 v[112:127], v[100:103], v[132:135], v[48:63]
	ds_read_b128 v[80:83], v204 offset:61440
	v_add_u32_e32 v217, s11, v209
	ds_read_b128 v[192:195], v217
	v_exp_f32_e32 v84, v84
	v_exp_f32_e32 v85, v85
	v_exp_f32_e32 v86, v86
	v_exp_f32_e32 v87, v87
	v_cvt_pk_bf16_f32 v220, v226, v227
	v_mfma_f32_32x32x16_bf16 v[112:127], v[96:99], v[128:131], v[112:127]
	v_cvt_pk_bf16_f32 v221, v228, v229
	v_mfma_f32_32x32x16_bf16 v[96:111], v[222:225], v[132:135], v[48:63]
	v_cvt_pk_bf16_f32 v222, v84, v85
	v_cvt_pk_bf16_f32 v223, v86, v87
	v_mfma_f32_32x32x16_bf16 v[32:47], v[144:147], v[174:177], v[32:47]
	v_add_u32_e32 v218, s11, v210
	v_exp_f32_e32 v88, v88
	v_exp_f32_e32 v89, v89
	v_exp_f32_e32 v90, v90
	v_exp_f32_e32 v91, v91
	s_waitcnt lgkmcnt(0)
	v_mfma_f32_32x32x16_bf16 v[112:127], v[80:83], v[140:143], v[112:127]
	ds_read_b128 v[80:83], v203 offset:61440
	ds_read_b128 v[84:87], v218
	s_waitcnt lgkmcnt(0)
	v_mfma_f32_32x32x16_bf16 v[112:127], v[80:83], v[136:139], v[112:127]
	v_exp_f32_e32 v80, v92
	v_exp_f32_e32 v81, v93
	v_exp_f32_e32 v82, v94
	v_exp_f32_e32 v83, v95
	v_cvt_pk_bf16_f32 v174, v88, v89
	v_cvt_pk_bf16_f32 v175, v90, v91
	v_cvt_pk_bf16_f32 v176, v80, v81
	v_mfma_f32_32x32x16_bf16 v[96:111], v[180:183], v[128:131], v[96:111]
	v_cvt_pk_bf16_f32 v177, v82, v83
	ds_read_b128 v[80:83], v206 offset:49152
	ds_read_b128 v[88:91], v206 offset:53248
	v_mfma_f32_32x32x16_bf16 v[96:111], v[192:195], v[140:143], v[96:111]
	s_waitcnt lgkmcnt(0)
	v_mfma_f32_32x32x16_bf16 v[0:15], v[88:91], v[220:223], v[0:15]
	ds_read_b128 v[92:95], v205 offset:49152
	ds_read_b128 v[180:183], v205 offset:53248
	v_exp_f32_e32 v193, v64
	v_exp_f32_e32 v194, v65
	v_exp_f32_e32 v195, v66
	v_exp_f32_e32 v192, v67
	v_exp_f32_e32 v229, v68
	v_exp_f32_e32 v230, v69
	v_mfma_f32_32x32x16_bf16 v[16:31], v[80:83], v[220:223], v[16:31]
	v_exp_f32_e32 v231, v70
	v_exp_f32_e32 v228, v71
	v_cvt_pk_bf16_f32 v64, v193, v194
	v_cvt_pk_bf16_f32 v65, v195, v192
	v_cvt_pk_bf16_f32 v66, v229, v230
	v_cvt_pk_bf16_f32 v67, v231, v228
	s_waitcnt lgkmcnt(0)
	v_mfma_f32_32x32x16_bf16 v[0:15], v[180:183], v[174:177], v[0:15]
	ds_read_b128 v[68:71], v200 offset:49152
	ds_read_b128 v[180:183], v200 offset:53248
	v_exp_f32_e32 v233, v72
	v_exp_f32_e32 v234, v73
	v_exp_f32_e32 v235, v74
	v_exp_f32_e32 v232, v75
	v_exp_f32_e32 v237, v76
	v_exp_f32_e32 v238, v77
	v_mfma_f32_32x32x16_bf16 v[16:31], v[92:95], v[174:177], v[16:31]
	v_exp_f32_e32 v239, v78
	v_exp_f32_e32 v236, v79
	v_cvt_pk_bf16_f32 v72, v233, v234
	v_cvt_pk_bf16_f32 v73, v235, v232
	v_cvt_pk_bf16_f32 v74, v237, v238
	v_cvt_pk_bf16_f32 v75, v239, v236
	v_mfma_f32_32x32x16_bf16 v[96:111], v[84:87], v[136:139], v[96:111]
	s_waitcnt lgkmcnt(0)
	v_mfma_f32_32x32x16_bf16 v[16:31], v[68:71], v[64:67], v[16:31]
	ds_read_b128 v[76:79], v151 offset:49152
	ds_read_b128 v[224:227], v151 offset:53248
	s_waitcnt lgkmcnt(0)
	v_mfma_f32_32x32x16_bf16 v[16:31], v[76:79], v[72:75], v[16:31]
	s_waitcnt vmcnt(2)
	s_mov_b32 m0, s6
	s_waitcnt lgkmcnt(0)
	s_barrier
; template <int TYPE, bool FIXREF>
; DI void attn_dense_unit(const Params& p, int layer, int head, int qb, char* lds, float bref) {
;     ...
;   for (int t = 0; t < NT - 4; t += 4) {
;     STEP(sA0, sA1, sB0, sB1, t, true, true, R0, R1, R3);
;     STEP(sB0, sB1, sA0, sA1, t + 1, true, true, R1, R2, R0);
;     STEP(sA0, sA1, sB0, sB1, t + 2, true, true, R2, R3, R1);
;     STEP(sB0, sB1, sA0, sA1, t + 3, true, true, R3, R0, R2);
;   }
	v_mfma_f32_32x32x16_bf16 v[0:15], v[180:183], v[64:67], v[0:15]
	v_lshl_add_u64 v[68:69], v[164:165], 0, s[44:45]
	global_load_lds_dwordx4 v[68:69], off
	v_lshl_add_u64 v[68:69], v[166:167], 0, s[46:47]
	s_mov_b32 m0, s7
	s_nop 0
	global_load_lds_dwordx4 v[68:69], off
	ds_read_b128 v[68:71], v201
	ds_read_b128 v[164:167], v201 offset:4096
	ds_read_b128 v[64:67], v202
	ds_read_b128 v[180:183], v202 offset:4096
	s_waitcnt lgkmcnt(0)
	v_mfma_f32_32x32x16_bf16 v[80:95], v[68:71], v[132:135], v[48:63]
	v_exp_f32_e32 v68, v112
	v_exp_f32_e32 v69, v113
	v_exp_f32_e32 v70, v114
	v_exp_f32_e32 v71, v115
	v_mfma_f32_32x32x16_bf16 v[32:47], v[144:147], v[220:223], v[32:47]
	v_mfma_f32_32x32x16_bf16 v[0:15], v[224:227], v[72:75], v[0:15]
	v_mfma_f32_32x32x16_bf16 v[80:95], v[64:67], v[128:131], v[80:95]
	v_exp_f32_e32 v64, v116
	v_exp_f32_e32 v65, v117
	v_exp_f32_e32 v66, v118
	v_exp_f32_e32 v67, v119
	v_cvt_pk_bf16_f32 v116, v68, v69
	v_cvt_pk_bf16_f32 v117, v70, v71
	v_cvt_pk_bf16_f32 v118, v64, v65
	v_cvt_pk_bf16_f32 v119, v66, v67
	v_mfma_f32_32x32x16_bf16 v[64:79], v[164:167], v[132:135], v[48:63]
	ds_read_b128 v[112:115], v204
	ds_read_b128 v[220:223], v204 offset:4096
	s_waitcnt lgkmcnt(0)
	v_mfma_f32_32x32x16_bf16 v[80:95], v[112:115], v[140:143], v[80:95]
	ds_read_b128 v[112:115], v203
	ds_read_b128 v[224:227], v203 offset:4096
	v_exp_f32_e32 v120, v120
	v_exp_f32_e32 v121, v121
	v_exp_f32_e32 v122, v122
	v_exp_f32_e32 v123, v123
	v_mfma_f32_32x32x16_bf16 v[32:47], v[144:147], v[174:177], v[32:47]
	v_mfma_f32_32x32x16_bf16 v[64:79], v[180:183], v[128:131], v[64:79]
	v_add_u32_e32 v166, 0, v211
	v_add_u32_e32 v167, s11, v211
	s_waitcnt lgkmcnt(0)
	v_mfma_f32_32x32x16_bf16 v[80:95], v[112:115], v[136:139], v[80:95]
	v_exp_f32_e32 v114, v124
	v_exp_f32_e32 v115, v125
	v_exp_f32_e32 v124, v126
	v_exp_f32_e32 v125, v127
	v_cvt_pk_bf16_f32 v112, v120, v121
	v_cvt_pk_bf16_f32 v113, v122, v123
	v_cvt_pk_bf16_f32 v114, v114, v115
	v_mfma_f32_32x32x16_bf16 v[64:79], v[220:223], v[140:143], v[64:79]
	v_cvt_pk_bf16_f32 v115, v124, v125
	ds_read_b128 v[120:123], v166 offset:61440
	ds_read_b128 v[124:127], v167
	s_waitcnt lgkmcnt(0)
	v_mfma_f32_32x32x16_bf16 v[0:15], v[124:127], v[116:119], v[0:15]
	v_add_u32_e32 v164, 0, v212
	v_add_u32_e32 v165, s11, v212
	ds_read_b128 v[174:177], v164 offset:61440
	ds_read_b128 v[180:183], v165
	v_exp_f32_e32 v127, v96
	v_exp_f32_e32 v222, v97
	v_exp_f32_e32 v223, v98
	v_mfma_f32_32x32x16_bf16 v[16:31], v[120:123], v[116:119], v[16:31]
	v_exp_f32_e32 v126, v99
	v_exp_f32_e32 v241, v100
	v_exp_f32_e32 v242, v101
	v_exp_f32_e32 v243, v102
	v_exp_f32_e32 v240, v103
	v_cvt_pk_bf16_f32 v96, v127, v222
	v_cvt_pk_bf16_f32 v97, v223, v126
	v_cvt_pk_bf16_f32 v98, v241, v242
	v_cvt_pk_bf16_f32 v99, v243, v240
	v_mfma_f32_32x32x16_bf16 v[32:47], v[144:147], v[116:119], v[32:47]
	v_exp_f32_e32 v125, v104
	v_exp_f32_e32 v104, v105
	v_exp_f32_e32 v105, v106
	v_exp_f32_e32 v124, v107
	v_pk_add_f32 v[106:107], v[162:163], v[156:157]
	v_pk_add_f32 v[168:169], v[184:185], v[168:169]
	v_pk_add_f32 v[106:107], v[170:171], v[106:107]
	v_pk_add_f32 v[168:169], v[188:189], v[168:169]
	v_pk_add_f32 v[106:107], v[186:187], v[106:107]
	v_pk_add_f32 v[168:169], v[190:191], v[168:169]
	v_pk_add_f32 v[106:107], v[106:107], v[192:193]
	s_waitcnt lgkmcnt(0)
	v_mfma_f32_32x32x16_bf16 v[0:15], v[180:183], v[112:115], v[0:15]
	v_add_f32_e64 v168, v168, v194
	v_add_f32_e64 v169, v169, v195
	v_add_f32_e64 v106, v228, v106
	v_add_f32_e64 v107, v229, v107
	v_add_f32_e64 v168, v230, v168
	v_add_f32_e64 v169, v231, v169
	v_pk_add_f32 v[106:107], v[232:233], v[106:107]
	v_pk_add_f32 v[168:169], v[234:235], v[168:169]
	v_pk_add_f32 v[106:107], v[236:237], v[106:107]
	v_add_u32_e32 v219, 0, v213
	v_mfma_f32_32x32x16_bf16 v[64:79], v[224:227], v[136:139], v[64:79]
	v_add_u32_e32 v220, s11, v213
	v_add_f32_e64 v168, v238, v168
	v_add_f32_e64 v169, v239, v169
	v_add_f32_e64 v106, v106, v126
	v_add_f32_e64 v107, v107, v127
	v_exp_f32_e32 v127, v108
	v_exp_f32_e32 v108, v109
	v_exp_f32_e32 v109, v110
	v_exp_f32_e32 v126, v111
	v_mfma_f32_32x32x16_bf16 v[16:31], v[174:177], v[112:115], v[16:31]
	ds_read_b128 v[100:103], v219 offset:61440
	ds_read_b128 v[120:123], v220
	v_add_f32_e64 v168, v168, v222
	v_add_f32_e64 v169, v169, v223
	v_add_f32_e64 v106, v240, v106
	v_add_f32_e64 v107, v241, v107
	v_pk_add_f32 v[168:169], v[242:243], v[168:169]
	v_pk_add_f32 v[106:107], v[124:125], v[106:107]
	v_pk_add_f32 v[168:169], v[104:105], v[168:169]
	v_mfma_f32_32x32x16_bf16 v[32:47], v[144:147], v[112:115], v[32:47]
	v_add_f32_e64 v162, v108, v168
	v_add_f32_e64 v163, v109, v169
	v_add_f32_e64 v156, v126, v106
	v_add_f32_e64 v157, v127, v107
	v_cvt_pk_bf16_f32 v104, v125, v104
	v_cvt_pk_bf16_f32 v105, v105, v124
	v_cvt_pk_bf16_f32 v106, v127, v108
	v_cvt_pk_bf16_f32 v107, v109, v126
	s_waitcnt lgkmcnt(0)
	v_mfma_f32_32x32x16_bf16 v[16:31], v[100:103], v[96:99], v[16:31]
	v_add_u32_e32 v168, 0, v214
	v_add_u32_e32 v169, s11, v214
	ds_read_b128 v[100:103], v168 offset:61440
	ds_read_b128 v[108:111], v169
	v_mfma_f32_32x32x16_bf16 v[0:15], v[120:123], v[96:99], v[0:15]
	s_waitcnt lgkmcnt(0)
	v_mfma_f32_32x32x16_bf16 v[16:31], v[100:103], v[104:107], v[16:31]
	v_mfma_f32_32x32x16_bf16 v[0:15], v[108:111], v[104:107], v[0:15]
	s_waitcnt vmcnt(2)
	s_waitcnt lgkmcnt(0)
	s_barrier
	s_add_i32 s9, s9, 4
	v_lshl_add_u64 v[158:159], v[158:159], 0, s[64:65]
	s_cmpk_lt_u32 s9, 0xf8
	v_lshl_add_u64 v[160:161], v[160:161], 0, s[66:67]
	s_cbranch_scc1 .LBB0_541
; template <int TYPE, bool FIXREF>
; DI void attn_dense_unit(const Params& p, int layer, int head, int qb, char* lds, float bref) {
;     ...
;   STEP(sA0, sA1, sB0, sB1, NT - 4, true, true, R0, R1, R3);
;   STEP(sB0, sB1, sA0, sA1, NT - 3, true, false, R1, R2, R0);
;   STEP(sA0, sA1, sB0, sB1, NT - 2, true, false, R2, R3, R1);
	s_mov_b64 s[0:1], 0xef10000
	s_mov_b32 m0, s10
	v_lshl_add_u64 v[96:97], v[154:155], 0, s[0:1]
	s_mov_b64 s[0:1], 0x7f80
	global_load_lds_dwordx4 v[96:97], off
	v_lshl_add_u64 v[96:97], v[152:153], 0, s[0:1]
	s_mov_b32 m0, s8
	s_mov_b64 s[88:89], 0x17618300
	global_load_lds_dwordx4 v[96:97], off
	ds_read_b128 v[96:99], v201 offset:20480
	ds_read_b128 v[144:147], v201 offset:24576
	s_mov_b64 s[62:63], 0x33ba200
	ds_read_b128 v[100:103], v202 offset:20480
	ds_read_b128 v[152:155], v202 offset:24576
	v_exp_f32_e32 v170, v80
	v_exp_f32_e32 v171, v81
	v_exp_f32_e32 v172, v82
	v_exp_f32_e32 v175, v83
	s_waitcnt lgkmcnt(0)
	v_mfma_f32_32x32x16_bf16 v[112:127], v[96:99], v[132:135], v[48:63]
	ds_read_b128 v[80:83], v204 offset:20480
	ds_read_b128 v[158:161], v204 offset:24576
	v_exp_f32_e32 v84, v84
	v_exp_f32_e32 v85, v85
	v_exp_f32_e32 v86, v86
	v_exp_f32_e32 v87, v87
	v_mfma_f32_32x32x16_bf16 v[112:127], v[100:103], v[128:131], v[112:127]
	v_cvt_pk_bf16_f32 v174, v170, v171
	v_cvt_pk_bf16_f32 v175, v172, v175
	v_cvt_pk_bf16_f32 v176, v84, v85
	v_cvt_pk_bf16_f32 v177, v86, v87
	v_mfma_f32_32x32x16_bf16 v[96:111], v[144:147], v[132:135], v[48:63]
	ds_read_b128 v[84:87], v203 offset:20480
	ds_read_b128 v[144:147], v203 offset:24576
	s_waitcnt lgkmcnt(0)
	v_mfma_f32_32x32x16_bf16 v[112:127], v[80:83], v[140:143], v[112:127]
	v_exp_f32_e32 v80, v88
	v_exp_f32_e32 v81, v89
	v_exp_f32_e32 v82, v90
	v_exp_f32_e32 v83, v91
	v_mfma_f32_32x32x16_bf16 v[112:127], v[84:87], v[136:139], v[112:127]
	v_exp_f32_e32 v84, v92
	v_exp_f32_e32 v85, v93
	v_exp_f32_e32 v86, v94
	v_exp_f32_e32 v87, v95
	v_cvt_pk_bf16_f32 v180, v80, v81
	v_cvt_pk_bf16_f32 v181, v82, v83
	v_cvt_pk_bf16_f32 v182, v84, v85
	v_mfma_f32_32x32x16_bf16 v[96:111], v[152:155], v[128:131], v[96:111]
	v_cvt_pk_bf16_f32 v183, v86, v87
	ds_read_b128 v[80:83], v206 offset:8192
	ds_read_b128 v[84:87], v206 offset:12288
	v_mfma_f32_32x32x16_bf16 v[96:111], v[158:161], v[140:143], v[96:111]
	s_waitcnt lgkmcnt(0)
	v_mfma_f32_32x32x16_bf16 v[0:15], v[84:87], v[174:177], v[0:15]
	ds_read_b128 v[88:91], v205 offset:8192
	ds_read_b128 v[92:95], v205 offset:12288
	v_exp_f32_e32 v153, v64
	v_exp_f32_e32 v171, v65
	v_exp_f32_e32 v184, v66
	v_exp_f32_e32 v152, v67
	v_exp_f32_e32 v170, v68
	v_exp_f32_e32 v172, v69
	v_exp_f32_e32 v186, v70
	v_exp_f32_e32 v154, v71
	v_mfma_f32_32x32x16_bf16 v[16:31], v[80:83], v[174:177], v[16:31]
	v_cvt_pk_bf16_f32 v64, v153, v171
	v_cvt_pk_bf16_f32 v65, v184, v152
	v_cvt_pk_bf16_f32 v66, v170, v172
	v_cvt_pk_bf16_f32 v67, v186, v154
	s_waitcnt lgkmcnt(0)
	v_mfma_f32_32x32x16_bf16 v[0:15], v[92:95], v[180:183], v[0:15]
	ds_read_b128 v[68:71], v200 offset:8192
	ds_read_b128 v[190:193], v200 offset:12288
	v_exp_f32_e32 v185, v72
	v_exp_f32_e32 v187, v73
	v_exp_f32_e32 v189, v74
	v_exp_f32_e32 v158, v75
	v_exp_f32_e32 v155, v76
	v_exp_f32_e32 v188, v77
	v_exp_f32_e32 v194, v78
	v_exp_f32_e32 v160, v79
	v_mfma_f32_32x32x16_bf16 v[96:111], v[144:147], v[136:139], v[96:111]
	v_cvt_pk_bf16_f32 v72, v185, v187
	v_cvt_pk_bf16_f32 v73, v189, v158
	v_cvt_pk_bf16_f32 v74, v155, v188
	v_cvt_pk_bf16_f32 v75, v194, v160
	v_mfma_f32_32x32x16_bf16 v[16:31], v[88:91], v[180:183], v[16:31]
	ds_read_b128 v[76:79], v151 offset:8192
	ds_read_b128 v[208:211], v151 offset:12288
	s_waitcnt lgkmcnt(0)
	v_mfma_f32_32x32x16_bf16 v[16:31], v[68:71], v[64:67], v[16:31]
	v_mfma_f32_32x32x16_bf16 v[16:31], v[76:79], v[72:75], v[16:31]
	s_waitcnt vmcnt(2)
	s_waitcnt lgkmcnt(0)
	s_barrier
	ds_read_b128 v[68:71], v201 offset:40960
	ds_read_b128 v[222:225], v201 offset:45056
	v_mfma_f32_32x32x16_bf16 v[0:15], v[190:193], v[64:67], v[0:15]
	v_mov_b64_e32 v[146:147], s[38:39]
	v_mov_b64_e32 v[144:145], s[36:37]
	v_exp_f32_e32 v159, v112
	v_exp_f32_e32 v161, v113
	v_exp_f32_e32 v195, v114
	v_exp_f32_e32 v207, v115
	v_mfma_f32_32x32x16_bf16 v[0:15], v[208:211], v[72:75], v[0:15]
	v_mfma_f32_32x32x16_bf16 v[32:47], v[144:147], v[174:177], v[32:47]
	ds_read_b128 v[64:67], v202 offset:40960
	ds_read_b128 v[174:177], v202 offset:45056
	s_waitcnt lgkmcnt(0)
	v_mfma_f32_32x32x16_bf16 v[80:95], v[68:71], v[132:135], v[48:63]
	ds_read_b128 v[112:115], v204 offset:40960
	ds_read_b128 v[190:193], v204 offset:45056
	v_exp_f32_e32 v116, v116
	v_exp_f32_e32 v117, v117
	v_exp_f32_e32 v118, v118
	v_exp_f32_e32 v119, v119
	v_mfma_f32_32x32x16_bf16 v[80:95], v[64:67], v[128:131], v[80:95]
	v_cvt_pk_bf16_f32 v208, v159, v161
	v_cvt_pk_bf16_f32 v209, v195, v207
	v_cvt_pk_bf16_f32 v210, v116, v117
	v_cvt_pk_bf16_f32 v211, v118, v119
	v_mfma_f32_32x32x16_bf16 v[64:79], v[222:225], v[132:135], v[48:63]
	s_waitcnt lgkmcnt(0)
	v_mfma_f32_32x32x16_bf16 v[80:95], v[112:115], v[140:143], v[80:95]
	ds_read_b128 v[112:115], v203 offset:40960
	ds_read_b128 v[222:225], v203 offset:45056
	v_exp_f32_e32 v116, v120
	v_exp_f32_e32 v117, v121
	v_exp_f32_e32 v118, v122
	v_exp_f32_e32 v119, v123
	v_mfma_f32_32x32x16_bf16 v[32:47], v[144:147], v[180:183], v[32:47]
	s_waitcnt lgkmcnt(0)
	v_mfma_f32_32x32x16_bf16 v[80:95], v[112:115], v[136:139], v[80:95]
	v_exp_f32_e32 v114, v126
	v_exp_f32_e32 v115, v127
	v_exp_f32_e32 v112, v124
	v_exp_f32_e32 v113, v125
	v_cvt_pk_bf16_f32 v120, v116, v117
	v_cvt_pk_bf16_f32 v123, v114, v115
	ds_read_b128 v[114:117], v206 offset:28672
	ds_read_b128 v[124:127], v206 offset:32768
	v_mfma_f32_32x32x16_bf16 v[64:79], v[174:177], v[128:131], v[64:79]
	v_cvt_pk_bf16_f32 v121, v118, v119
	v_cvt_pk_bf16_f32 v122, v112, v113
	v_mfma_f32_32x32x16_bf16 v[64:79], v[190:193], v[140:143], v[64:79]
	s_waitcnt lgkmcnt(0)
; template <int TYPE, bool FIXREF>
; DI void attn_dense_unit(const Params& p, int layer, int head, int qb, char* lds, float bref) {
;     ...
;   STEP(sB0, sB1, sA0, sA1, NT - 3, true, false, R1, R2, R0);
;   STEP(sA0, sA1, sB0, sB1, NT - 2, true, false, R2, R3, R1);
;   STEP(sB0, sB1, sA0, sA1, NT - 1, false, false, R3, R0, R2);
	v_mfma_f32_32x32x16_bf16 v[0:15], v[124:127], v[208:211], v[0:15]
	ds_read_b128 v[174:177], v205 offset:28672
	ds_read_b128 v[180:183], v205 offset:32768
	v_exp_f32_e32 v159, v96
	v_exp_f32_e32 v195, v97
	v_exp_f32_e32 v207, v98
	v_exp_f32_e32 v112, v99
	v_exp_f32_e32 v161, v100
	v_exp_f32_e32 v221, v101
	v_mfma_f32_32x32x16_bf16 v[16:31], v[114:117], v[208:211], v[16:31]
	v_exp_f32_e32 v226, v102
	v_exp_f32_e32 v114, v103
	v_cvt_pk_bf16_f32 v124, v159, v195
	v_cvt_pk_bf16_f32 v125, v207, v112
	v_cvt_pk_bf16_f32 v126, v161, v221
	v_cvt_pk_bf16_f32 v127, v226, v114
	s_waitcnt lgkmcnt(0)
	v_mfma_f32_32x32x16_bf16 v[0:15], v[180:183], v[120:123], v[0:15]
	ds_read_b128 v[96:99], v200 offset:28672
	ds_read_b128 v[180:183], v200 offset:32768
	v_exp_f32_e32 v113, v104
	v_exp_f32_e32 v227, v105
	v_exp_f32_e32 v228, v106
	v_exp_f32_e32 v116, v107
	v_exp_f32_e32 v115, v108
	v_exp_f32_e32 v229, v109
	v_exp_f32_e32 v230, v110
	v_exp_f32_e32 v118, v111
	v_mfma_f32_32x32x16_bf16 v[64:79], v[222:225], v[136:139], v[64:79]
	v_cvt_pk_bf16_f32 v190, v113, v227
	v_cvt_pk_bf16_f32 v191, v228, v116
	v_cvt_pk_bf16_f32 v192, v115, v229
	v_cvt_pk_bf16_f32 v193, v230, v118
	v_mfma_f32_32x32x16_bf16 v[16:31], v[174:177], v[120:123], v[16:31]
	ds_read_b128 v[100:103], v151 offset:28672
	ds_read_b128 v[174:177], v151 offset:32768
	s_waitcnt lgkmcnt(0)
	v_mfma_f32_32x32x16_bf16 v[16:31], v[96:99], v[124:127], v[16:31]
	v_mfma_f32_32x32x16_bf16 v[16:31], v[100:103], v[190:193], v[16:31]
	s_waitcnt vmcnt(0)
	s_waitcnt lgkmcnt(0)
	s_barrier
	ds_read_b128 v[222:225], v201 offset:61440
	ds_read_b128 v[212:215], v215
	v_mfma_f32_32x32x16_bf16 v[0:15], v[180:183], v[124:127], v[0:15]
	ds_read_b128 v[124:127], v202 offset:61440
	ds_read_b128 v[180:183], v216
	v_exp_f32_e32 v117, v80
	v_exp_f32_e32 v119, v81
	v_exp_f32_e32 v201, v82
	v_exp_f32_e32 v202, v83
	v_mfma_f32_32x32x16_bf16 v[0:15], v[174:177], v[190:193], v[0:15]
	s_waitcnt lgkmcnt(0)
	v_mfma_f32_32x32x16_bf16 v[96:111], v[222:225], v[132:135], v[48:63]
	v_mfma_f32_32x32x16_bf16 v[32:47], v[144:147], v[208:211], v[32:47]
	ds_read_b128 v[80:83], v204 offset:61440
	ds_read_b128 v[174:177], v217
	v_mfma_f32_32x32x16_bf16 v[96:111], v[124:127], v[128:131], v[96:111]
	v_exp_f32_e32 v124, v84
	v_exp_f32_e32 v125, v85
	v_exp_f32_e32 v126, v86
	v_exp_f32_e32 v87, v87
	v_cvt_pk_bf16_f32 v84, v117, v119
	v_cvt_pk_bf16_f32 v85, v201, v202
	v_cvt_pk_bf16_f32 v86, v124, v125
	v_cvt_pk_bf16_f32 v87, v126, v87
	v_mfma_f32_32x32x16_bf16 v[48:63], v[212:215], v[132:135], v[48:63]
	s_waitcnt lgkmcnt(0)
	v_mfma_f32_32x32x16_bf16 v[96:111], v[80:83], v[140:143], v[96:111]
	ds_read_b128 v[80:83], v203 offset:61440
	ds_read_b128 v[124:127], v218
	v_exp_f32_e32 v88, v88
	v_exp_f32_e32 v89, v89
	v_exp_f32_e32 v90, v90
	v_exp_f32_e32 v91, v91
	v_mfma_f32_32x32x16_bf16 v[32:47], v[144:147], v[120:123], v[32:47]
	s_waitcnt lgkmcnt(0)
	v_mfma_f32_32x32x16_bf16 v[96:111], v[80:83], v[136:139], v[96:111]
	v_exp_f32_e32 v82, v92
	v_exp_f32_e32 v83, v93
	v_exp_f32_e32 v92, v94
	v_exp_f32_e32 v93, v95
	v_cvt_pk_bf16_f32 v80, v88, v89
	v_cvt_pk_bf16_f32 v81, v90, v91
	v_cvt_pk_bf16_f32 v82, v82, v83
	v_mfma_f32_32x32x16_bf16 v[48:63], v[180:183], v[128:131], v[48:63]
	v_cvt_pk_bf16_f32 v83, v92, v93
	ds_read_b128 v[88:91], v206 offset:49152
	ds_read_b128 v[92:95], v206 offset:53248
	v_mfma_f32_32x32x16_bf16 v[48:63], v[174:177], v[140:143], v[48:63]
	s_waitcnt lgkmcnt(0)
	v_mfma_f32_32x32x16_bf16 v[0:15], v[92:95], v[84:87], v[0:15]
	ds_read_b128 v[120:123], v205 offset:49152
	ds_read_b128 v[128:131], v205 offset:53248
	v_exp_f32_e32 v117, v64
	v_exp_f32_e32 v132, v65
	v_exp_f32_e32 v133, v66
	v_exp_f32_e32 v64, v67
	v_exp_f32_e32 v119, v68
	v_exp_f32_e32 v134, v69
	v_exp_f32_e32 v135, v70
	v_exp_f32_e32 v66, v71
	v_mfma_f32_32x32x16_bf16 v[16:31], v[88:91], v[84:87], v[16:31]
	v_cvt_pk_bf16_f32 v88, v117, v132
	v_cvt_pk_bf16_f32 v89, v133, v64
	v_cvt_pk_bf16_f32 v90, v119, v134
	v_cvt_pk_bf16_f32 v91, v135, v66
	s_waitcnt lgkmcnt(0)
	v_mfma_f32_32x32x16_bf16 v[0:15], v[128:131], v[80:83], v[0:15]
	ds_read_b128 v[92:95], v200 offset:49152
	ds_read_b128 v[128:131], v200 offset:53248
	v_exp_f32_e32 v65, v72
	v_exp_f32_e32 v140, v73
	v_exp_f32_e32 v141, v74
	v_exp_f32_e32 v68, v75
	v_exp_f32_e32 v67, v76
	v_exp_f32_e32 v70, v79
	v_mfma_f32_32x32x16_bf16 v[48:63], v[124:127], v[136:139], v[48:63]
	v_exp_f32_e32 v124, v77
	v_exp_f32_e32 v125, v78
	v_cvt_pk_bf16_f32 v72, v65, v140
	v_cvt_pk_bf16_f32 v73, v141, v68
	v_cvt_pk_bf16_f32 v74, v67, v124
	v_cvt_pk_bf16_f32 v75, v125, v70
	v_mfma_f32_32x32x16_bf16 v[16:31], v[120:123], v[80:83], v[16:31]
	ds_read_b128 v[76:79], v151 offset:49152
	ds_read_b128 v[120:123], v151 offset:53248
	s_waitcnt lgkmcnt(0)
	v_mfma_f32_32x32x16_bf16 v[16:31], v[92:95], v[88:91], v[16:31]
	v_mfma_f32_32x32x16_bf16 v[16:31], v[76:79], v[72:75], v[16:31]
	s_waitcnt vmcnt(0)
	s_waitcnt lgkmcnt(0)
	s_barrier
; template <int TYPE, bool FIXREF>
; DI void attn_dense_unit(const Params& p, int layer, int head, int qb, char* lds, float bref) {
;     ...
;   STEP(sB0, sB1, sA0, sA1, NT - 1, false, false, R3, R0, R2);
;   lsum += ls0 + ls1 + ls2;
;   const float l = (NONES > 0 ? la[0] : 0.f) + lsum + __shfl_xor(lsum, 32);
	v_mfma_f32_32x32x16_bf16 v[0:15], v[128:131], v[88:91], v[0:15]
	v_exp_f32_e32 v69, v96
	v_exp_f32_e32 v71, v97
	v_exp_f32_e32 v77, v98
	v_exp_f32_e32 v78, v99
	v_mfma_f32_32x32x16_bf16 v[32:47], v[144:147], v[84:87], v[32:47]
	v_exp_f32_e32 v79, v100
	v_exp_f32_e32 v84, v101
	v_exp_f32_e32 v85, v102
	v_exp_f32_e32 v86, v103
	v_mfma_f32_32x32x16_bf16 v[32:47], v[144:147], v[80:83], v[32:47]
	v_cvt_pk_bf16_f32 v76, v69, v71
	v_cvt_pk_bf16_f32 v77, v77, v78
	v_cvt_pk_bf16_f32 v78, v79, v84
	v_cvt_pk_bf16_f32 v79, v85, v86
	v_exp_f32_e32 v69, v104
	v_exp_f32_e32 v71, v105
	v_exp_f32_e32 v80, v106
	v_exp_f32_e32 v81, v107
	v_exp_f32_e32 v82, v108
	v_exp_f32_e32 v83, v109
	v_exp_f32_e32 v84, v110
	v_exp_f32_e32 v85, v111
	v_mfma_f32_32x32x16_bf16 v[0:15], v[120:123], v[72:75], v[0:15]
	v_cvt_pk_bf16_f32 v73, v80, v81
	v_cvt_pk_bf16_f32 v74, v82, v83
	v_cvt_pk_bf16_f32 v75, v84, v85
	ds_read_b128 v[80:83], v166 offset:61440
	ds_read_b128 v[84:87], v167
	v_cvt_pk_bf16_f32 v72, v69, v71
	s_waitcnt lgkmcnt(0)
	v_mfma_f32_32x32x16_bf16 v[0:15], v[84:87], v[76:79], v[0:15]
	ds_read_b128 v[84:87], v164 offset:61440
	ds_read_b128 v[88:91], v165
	v_mfma_f32_32x32x16_bf16 v[16:31], v[80:83], v[76:79], v[16:31]
	v_exp_f32_e32 v69, v48
	v_add_f32_e32 v48, v163, v184
	v_add_f32_e32 v48, v186, v48
	v_add_f32_e32 v48, v189, v48
	v_add_f32_e32 v48, v194, v48
	v_add_f32_e32 v48, v48, v207
	v_add_f32_e32 v48, v226, v48
	v_add_f32_e32 v48, v228, v48
	v_add_f32_e32 v48, v230, v48
	s_waitcnt lgkmcnt(0)
	v_mfma_f32_32x32x16_bf16 v[0:15], v[88:91], v[72:75], v[0:15]
	v_exp_f32_e32 v88, v59
	v_exp_f32_e32 v59, v50
	v_add_f32_e32 v48, v48, v133
	v_exp_f32_e32 v71, v52
	v_exp_f32_e32 v52, v53
	v_exp_f32_e32 v53, v54
	v_add_f32_e32 v48, v135, v48
	v_mfma_f32_32x32x16_bf16 v[16:31], v[84:87], v[72:75], v[16:31]
	v_exp_f32_e32 v85, v56
	v_exp_f32_e32 v56, v58
	v_add_f32_e32 v48, v141, v48
	v_exp_f32_e32 v58, v62
	v_add_f32_e32 v48, v125, v48
	v_add_f32_e32 v48, v48, v59
	v_add_f32_e32 v48, v53, v48
	v_add_f32_e32 v48, v56, v48
	v_add_f32_e32 v91, v58, v48
	v_add_f32_e32 v48, v162, v171
	v_add_f32_e32 v48, v172, v48
	v_add_f32_e32 v48, v187, v48
	v_add_f32_e32 v48, v188, v48
	v_add_f32_e32 v48, v48, v195
	v_add_f32_e32 v48, v221, v48
	v_add_f32_e32 v48, v227, v48
	v_add_f32_e32 v48, v229, v48
	v_exp_f32_e32 v86, v55
	v_exp_f32_e32 v55, v49
	v_add_f32_e32 v48, v48, v132
	v_add_f32_e32 v48, v134, v48
	v_exp_f32_e32 v54, v57
	v_add_f32_e32 v48, v140, v48
	v_exp_f32_e32 v57, v61
	v_add_f32_e32 v48, v124, v48
	v_mfma_f32_32x32x16_bf16 v[32:47], v[144:147], v[76:79], v[32:47]
	v_add_f32_e32 v48, v48, v55
	v_add_f32_e32 v48, v52, v48
	v_add_f32_e32 v48, v54, v48
	ds_read_b128 v[80:83], v219 offset:61440
	ds_read_b128 v[92:95], v220
	v_add_f32_e32 v89, v57, v48
	v_add_f32_e32 v48, v157, v153
	v_exp_f32_e32 v84, v51
	v_exp_f32_e32 v90, v63
	v_exp_f32_e32 v87, v60
	v_add_f32_e32 v153, v170, v48
	v_mov_b32_e32 v157, v185
	v_pk_add_f32 v[48:49], v[156:157], v[152:153]
	v_mfma_f32_32x32x16_bf16 v[32:47], v[144:147], v[72:75], v[32:47]
	v_add_f32_e64 v48, v154, v48
	v_add_f32_e64 v49, v155, v49
	v_add_f32_e64 v48, v158, v48
	v_add_f32_e64 v49, v159, v49
	v_add_f32_e64 v50, v160, v48
	v_add_f32_e64 v51, v161, v49
	s_nop 5
	v_cvt_pk_bf16_f32 v34, v69, v55
	v_cvt_pk_bf16_f32 v35, v59, v84
	v_cvt_pk_bf16_f32 v36, v71, v52
	v_cvt_pk_bf16_f32 v37, v53, v86
	v_cvt_pk_bf16_f32 v38, v85, v54
	v_cvt_pk_bf16_f32 v39, v56, v88
	v_cvt_pk_bf16_f32 v40, v87, v57
	v_cvt_pk_bf16_f32 v41, v58, v90
	s_waitcnt lgkmcnt(0)
	v_mfma_f32_32x32x16_bf16 v[0:15], v[92:95], v[34:37], v[0:15]
	ds_read_b128 v[42:45], v168 offset:61440
	ds_read_b128 v[46:49], v169
	v_mfma_f32_32x32x16_bf16 v[16:31], v[80:83], v[34:37], v[16:31]
	s_waitcnt lgkmcnt(0)
	v_mfma_f32_32x32x16_bf16 v[0:15], v[46:49], v[38:41], v[0:15]
	v_mfma_f32_32x32x16_bf16 v[16:31], v[42:45], v[38:41], v[16:31]
	v_add_f32_e64 v34, v50, v112
	v_add_f32_e64 v35, v51, v113
	v_lshlrev_b32_e32 v172, 1, v150
	v_add_f32_e64 v34, v114, v34
	v_add_f32_e64 v35, v115, v35
	s_waitcnt vmcnt(0)
	s_waitcnt lgkmcnt(0)
	s_barrier
; DI unsigned pk2(float lo, float hi) { f32x2 v = {lo, hi}; bf16x2_t b = __builtin_convertvector(v, bf16x2_t); return __builtin_bit_cast(unsigned, b); }
; DI void store_o_wide(bf16_t* rowp, const f32x16& o, float inv, int h) {
; #pragma unroll
;   for (int pr = 0; pr < 2; ++pr) {
;     const int g = 2 * pr;
;     const unsigned ax = pk2(o[4 * g] * inv, o[4 * g + 1] * inv), ay = pk2(o[4 * g + 2] * inv, o[4 * g + 3] * inv);
;     const unsigned bx = pk2(o[4 * g + 4] * inv, o[4 * g + 5] * inv), by = pk2(o[4 * g + 6] * inv, o[4 * g + 7] * inv);
;     const auto sx = __builtin_amdgcn_permlane32_swap(ax, bx, false, false);
;     const auto sy = __builtin_amdgcn_permlane32_swap(ay, by, false, false);
;     const u32x4 w = {sx[0], sy[0], sx[1], sy[1]};
;     *(u32x4*)(rowp + 8 * (g + h)) = w;
;   }
; template <int TYPE, bool FIXREF>
; DI void attn_dense_unit(const Params& p, int layer, int head, int qb, char* lds, float bref) {
;     ...
;   lsum += ls0 + ls1 + ls2;
;   const float l = (NONES > 0 ? la[0] : 0.f) + lsum + __shfl_xor(lsum, 32);
;     ...
;   const float inv = 1.0f / l;
;   bf16_t* op = O + (size_t)q * 512 + head * 64;
;   store_o_wide(op, o0, inv, h); store_o_wide(op + 32, o1, inv, h);
	v_pk_add_f32 v[34:35], v[116:117], v[34:35]
	s_nop 0
	v_pk_add_f32 v[34:35], v[118:119], v[34:35]
	s_nop 0
	v_pk_add_f32 v[34:35], v[34:35], v[64:65]
	s_nop 0
	v_pk_add_f32 v[34:35], v[66:67], v[34:35]
	s_nop 0
	v_pk_add_f32 v[34:35], v[68:69], v[34:35]
	s_nop 0
	v_pk_add_f32 v[34:35], v[70:71], v[34:35]
	s_nop 0
	v_pk_add_f32 v[34:35], v[34:35], v[84:85]
	s_nop 0
	v_pk_add_f32 v[34:35], v[86:87], v[34:35]
	s_nop 0
	v_pk_add_f32 v[34:35], v[88:89], v[34:35]
	s_nop 0
	v_pk_add_f32 v[34:35], v[90:91], v[34:35]
	s_nop 0
	v_add_f32_e32 v33, v34, v35
	ds_bpermute_b32 v34, v199, v33
	v_add_f32_e32 v32, v33, v32
	s_waitcnt lgkmcnt(0)
	v_add_f32_e32 v32, v32, v34
	v_div_scale_f32 v33, s[0:1], v32, v32, 1.0
	v_rcp_f32_e32 v34, v33
	v_readlane_b32 s0, v253, 13
	v_readlane_b32 s1, v253, 14
	v_fma_f32 v35, -v33, v34, 1.0
	v_fmac_f32_e32 v34, v35, v34
	v_div_scale_f32 v35, vcc, 1.0, v32, 1.0
	v_mul_f32_e32 v36, v35, v34
	v_fma_f32 v37, -v33, v36, v35
	v_fmac_f32_e32 v36, v37, v34
	v_fma_f32 v33, -v33, v36, v35
	v_div_fmas_f32 v33, v33, v34, v36
	v_div_fixup_f32 v32, v33, v32, 1.0
	v_lshlrev_b64 v[34:35], 10, v[148:149]
	v_pk_mul_f32 v[16:17], v[16:17], v[32:33] op_sel_hi:[1,0]
	v_pk_mul_f32 v[18:19], v[18:19], v[32:33] op_sel_hi:[1,0]
	v_pk_mul_f32 v[0:1], v[0:1], v[32:33] op_sel_hi:[1,0]
	v_pk_mul_f32 v[2:3], v[2:3], v[32:33] op_sel_hi:[1,0]
	v_lshl_add_u64 v[34:35], s[0:1], 0, v[34:35]
	v_cvt_pk_bf16_f32 v16, v16, v17
	v_cvt_pk_bf16_f32 v17, v18, v19
	v_pk_mul_f32 v[18:19], v[20:21], v[32:33] op_sel_hi:[1,0]
	v_pk_mul_f32 v[20:21], v[22:23], v[32:33] op_sel_hi:[1,0]
	v_cvt_pk_bf16_f32 v0, v0, v1
	v_cvt_pk_bf16_f32 v1, v2, v3
	v_pk_mul_f32 v[2:3], v[4:5], v[32:33] op_sel_hi:[1,0]
	v_pk_mul_f32 v[4:5], v[6:7], v[32:33] op_sel_hi:[1,0]
	v_lshl_add_u64 v[34:35], v[34:35], 0, s[68:69]
	v_cvt_pk_bf16_f32 v18, v18, v19
	v_cvt_pk_bf16_f32 v19, v20, v21
	v_cvt_pk_bf16_f32 v2, v2, v3
	v_cvt_pk_bf16_f32 v3, v4, v5
	v_permlane32_swap_b32_e32 v16, v18
	v_permlane32_swap_b32_e32 v17, v19
	v_lshl_add_u64 v[20:21], v[34:35], 0, v[172:173]
	v_permlane32_swap_b32_e32 v0, v2
	v_permlane32_swap_b32_e32 v1, v3
	global_store_dwordx4 v[20:21], v[16:19], off
	global_store_dwordx4 v[20:21], v[0:3], off offset:64
	v_pk_mul_f32 v[22:23], v[30:31], v[32:33] op_sel_hi:[1,0]
	v_pk_mul_f32 v[16:17], v[24:25], v[32:33] op_sel_hi:[1,0]
	v_pk_mul_f32 v[18:19], v[26:27], v[32:33] op_sel_hi:[1,0]
	v_pk_mul_f32 v[0:1], v[8:9], v[32:33] op_sel_hi:[1,0]
	v_pk_mul_f32 v[2:3], v[10:11], v[32:33] op_sel_hi:[1,0]
	v_cvt_pk_bf16_f32 v16, v16, v17
	v_cvt_pk_bf16_f32 v17, v18, v19
	v_pk_mul_f32 v[18:19], v[28:29], v[32:33] op_sel_hi:[1,0]
	v_cvt_pk_bf16_f32 v0, v0, v1
	v_cvt_pk_bf16_f32 v1, v2, v3
	v_pk_mul_f32 v[2:3], v[12:13], v[32:33] op_sel_hi:[1,0]
	v_pk_mul_f32 v[6:7], v[14:15], v[32:33] op_sel_hi:[1,0]
	v_cvt_pk_bf16_f32 v18, v18, v19
	v_cvt_pk_bf16_f32 v19, v22, v23
	v_cvt_pk_bf16_f32 v2, v2, v3
	v_cvt_pk_bf16_f32 v3, v6, v7
	v_permlane32_swap_b32_e32 v16, v18
	v_permlane32_swap_b32_e32 v17, v19
	v_lshl_add_u64 v[4:5], v[20:21], 0, 64
	v_permlane32_swap_b32_e32 v0, v2
	v_permlane32_swap_b32_e32 v1, v3
	global_store_dwordx4 v[20:21], v[16:19], off offset:32
